# P1 RMSNorm row loads batched (without K-norm change)
# speedup vs baseline: 1.1028x; 1.0093x over previous
.LBB0_83:
	s_or_b64 exec, exec, s[10:11]
	v_lshl_add_u64 v[2:3], v[2:3], 0, v[50:51]
	global_load_dwordx4 v[30:33], v[2:3], off
	global_load_dwordx4 v[26:29], v[2:3], off offset:1024
	global_load_dwordx4 v[22:25], v[2:3], off offset:2048
	global_load_dwordx4 v[18:21], v[2:3], off offset:3072
	v_add_co_u32_e32 v2, vcc, s16, v2
	v_min_i32_e32 v81, 0x4000, v34
	s_nop 0
	v_addc_co_u32_e32 v3, vcc, 0, v3, vcc
	global_load_dwordx4 v[14:17], v[2:3], off
	global_load_dwordx4 v[6:9], v[2:3], off offset:1024
	global_load_dwordx4 v[82:85], v[2:3], off offset:2048
	global_load_dwordx4 v[86:89], v[2:3], off offset:3072
	v_ashrrev_i32_e32 v81, 11, v81
	v_mul_i32_i24_e32 v68, 0x1800, v81
	v_ashrrev_i32_e32 v69, 31, v68
	v_lshl_add_u64 v[68:69], v[68:69], 2, s[6:7]
	v_lshlrev_b64 v[72:73], 12, v[72:73]
	v_lshl_add_u64 v[34:35], v[34:35], 0, s[88:89]
	v_cmp_lt_i32_e32 vcc, s12, v34
	s_or_b64 s[8:9], vcc, s[8:9]
	v_lshl_add_u64 v[48:49], v[48:49], 0, s[14:15]
	v_lshl_add_u64 v[74:75], v[68:69], 0, v[50:51]
	v_lshl_add_u64 v[70:71], v[68:69], 0, s[22:23]
	v_lshl_add_u64 v[90:91], v[70:71], 0, v[50:51]
	v_lshl_add_u64 v[4:5], v[68:69], 0, v[58:59]
	v_lshl_add_u64 v[10:11], v[70:71], 0, v[58:59]
	v_lshl_add_u64 v[92:93], v[46:47], 0, v[72:73]
	global_load_dwordx4 v[94:97], v[36:37], off
	global_load_dwordx4 v[126:129], v[74:75], off
	global_load_dwordx4 v[158:161], v[90:91], off
	global_load_dwordx4 v[98:101], v[36:37], off offset:1024
	global_load_dwordx4 v[130:133], v[74:75], off offset:1024
	global_load_dwordx4 v[162:165], v[90:91], off offset:1024
	global_load_dwordx4 v[102:105], v[36:37], off offset:2048
	global_load_dwordx4 v[134:137], v[74:75], off offset:2048
	global_load_dwordx4 v[166:169], v[90:91], off offset:2048
	global_load_dwordx4 v[106:109], v[36:37], off offset:3072
	global_load_dwordx4 v[138:141], v[74:75], off offset:3072
	global_load_dwordx4 v[170:173], v[90:91], off offset:3072
	global_load_dwordx4 v[110:113], v[38:39], off
	global_load_dwordx4 v[142:145], v[4:5], off
	global_load_dwordx4 v[174:177], v[10:11], off
	global_load_dwordx4 v[114:117], v[38:39], off offset:1024
	global_load_dwordx4 v[146:149], v[4:5], off offset:1024
	global_load_dwordx4 v[178:181], v[10:11], off offset:1024
	global_load_dwordx4 v[118:121], v[38:39], off offset:2048
	global_load_dwordx4 v[150:153], v[4:5], off offset:2048
	global_load_dwordx4 v[182:185], v[10:11], off offset:2048
	global_load_dwordx4 v[122:125], v[38:39], off offset:3072
	global_load_dwordx4 v[154:157], v[4:5], off offset:3072
	global_load_dwordx4 v[186:189], v[10:11], off offset:3072
	s_waitcnt vmcnt(24)
	v_mul_f32_e32 v4, v31, v31
	v_mul_f32_e32 v5, v27, v27
	v_fmac_f32_e32 v4, v30, v30
	v_fmac_f32_e32 v5, v26, v26
	v_fmac_f32_e32 v4, v32, v32
	v_fmac_f32_e32 v5, v28, v28
	v_fmac_f32_e32 v4, v33, v33
	v_fmac_f32_e32 v5, v29, v29
	v_add_f32_e32 v4, v4, v5
	v_mul_f32_e32 v5, v23, v23
	v_fmac_f32_e32 v5, v22, v22
	v_fmac_f32_e32 v5, v24, v24
	v_fmac_f32_e32 v5, v25, v25
	v_add_f32_e32 v4, v4, v5
	v_mul_f32_e32 v5, v19, v19
	v_fmac_f32_e32 v5, v18, v18
	v_fmac_f32_e32 v5, v20, v20
	v_fmac_f32_e32 v5, v21, v21
	v_mov_b32_e32 v10, v15
	v_mov_b32_e32 v11, v7
	v_add_f32_e32 v12, v4, v5
	v_mov_b32_e32 v4, v14
	v_mov_b32_e32 v5, v6
	v_pk_mul_f32 v[10:11], v[10:11], v[10:11]
	s_nop 0
	v_pk_fma_f32 v[4:5], v[4:5], v[4:5], v[10:11]
	v_mov_b32_e32 v10, v16
	v_mov_b32_e32 v11, v8
	v_pk_fma_f32 v[4:5], v[10:11], v[10:11], v[4:5]
	v_mov_b32_e32 v10, v17
	v_mov_b32_e32 v11, v9
	v_pk_fma_f32 v[4:5], v[10:11], v[10:11], v[4:5]
	s_nop 0
	v_add_f32_e32 v4, v12, v4
	v_add_f32_e32 v66, v4, v5
	v_mov_b32_e32 v74, v83
	v_mov_b32_e32 v75, v87
	v_mov_b32_e32 v70, v82
	v_mov_b32_e32 v71, v86
	v_pk_mul_f32 v[74:75], v[74:75], v[74:75]
	s_nop 0
	v_pk_fma_f32 v[70:71], v[70:71], v[70:71], v[74:75]
	v_mov_b32_e32 v74, v84
	v_mov_b32_e32 v75, v88
	v_pk_fma_f32 v[70:71], v[74:75], v[74:75], v[70:71]
	v_mov_b32_e32 v74, v85
	v_mov_b32_e32 v75, v89
	v_pk_fma_f32 v[70:71], v[74:75], v[74:75], v[70:71]
	s_nop 0
	v_add_f32_e32 v66, v66, v70
	v_add_f32_e32 v66, v66, v71
	ds_bpermute_b32 v70, v67, v66
	s_waitcnt lgkmcnt(0)
	v_add_f32_e32 v66, v66, v70
	ds_bpermute_b32 v70, v76, v66
	s_waitcnt lgkmcnt(0)
	v_add_f32_e32 v66, v66, v70
	ds_bpermute_b32 v70, v77, v66
	s_waitcnt lgkmcnt(0)
	v_add_f32_e32 v66, v66, v70
	ds_bpermute_b32 v70, v78, v66
	s_waitcnt lgkmcnt(0)
	v_add_f32_e32 v66, v66, v70
	ds_bpermute_b32 v70, v79, v66
	s_waitcnt lgkmcnt(0)
	v_add_f32_e32 v66, v66, v70
	ds_bpermute_b32 v70, v80, v66
	s_waitcnt lgkmcnt(0)
	v_add_f32_e32 v66, v66, v70
	v_fmamk_f32 v66, v66, 0x3a000000, v230
	v_cmp_gt_f32_e32 vcc, s70, v66
	v_mul_f32_e32 v70, 0x4b800000, v66
	s_nop 0
	v_cndmask_b32_e32 v66, v66, v70, vcc
	v_rsq_f32_e32 v66, v66
	s_nop 0
	v_mul_f32_e32 v70, 0x45800000, v66
	v_cndmask_b32_e32 v66, v66, v70, vcc
	v_pk_mul_f32 v[30:31], v[30:31], v[66:67] op_sel_hi:[1,0]
	v_pk_mul_f32 v[32:33], v[32:33], v[66:67] op_sel_hi:[1,0]
	v_pk_mul_f32 v[26:27], v[26:27], v[66:67] op_sel_hi:[1,0]
	v_pk_mul_f32 v[28:29], v[28:29], v[66:67] op_sel_hi:[1,0]
	v_pk_mul_f32 v[22:23], v[22:23], v[66:67] op_sel_hi:[1,0]
	v_pk_mul_f32 v[24:25], v[24:25], v[66:67] op_sel_hi:[1,0]
	v_pk_mul_f32 v[18:19], v[18:19], v[66:67] op_sel_hi:[1,0]
	v_pk_mul_f32 v[20:21], v[20:21], v[66:67] op_sel_hi:[1,0]
	v_pk_mul_f32 v[14:15], v[14:15], v[66:67] op_sel_hi:[1,0]
	v_pk_mul_f32 v[16:17], v[16:17], v[66:67] op_sel_hi:[1,0]
	v_pk_mul_f32 v[6:7], v[6:7], v[66:67] op_sel_hi:[1,0]
	v_pk_mul_f32 v[8:9], v[8:9], v[66:67] op_sel_hi:[1,0]
	v_pk_mul_f32 v[82:83], v[82:83], v[66:67] op_sel_hi:[1,0]
	v_pk_mul_f32 v[84:85], v[84:85], v[66:67] op_sel_hi:[1,0]
	v_pk_mul_f32 v[86:87], v[86:87], v[66:67] op_sel_hi:[1,0]
	v_pk_mul_f32 v[88:89], v[88:89], v[66:67] op_sel_hi:[1,0]
	s_waitcnt vmcnt(21)
	v_pk_mul_f32 v[30:31], v[94:95], v[30:31]
	v_pk_mul_f32 v[32:33], v[96:97], v[32:33]
	v_pk_add_f32 v[4:5], v[158:159], 1.0 op_sel_hi:[1,0]
	v_pk_add_f32 v[10:11], v[160:161], 1.0 op_sel_hi:[1,0]
	v_pk_fma_f32 v[30:31], v[4:5], v[30:31], v[126:127]
	v_pk_fma_f32 v[32:33], v[10:11], v[32:33], v[128:129]
	v_cvt_pk_bf16_f32 v12, v30, v31
	v_cvt_pk_bf16_f32 v13, v32, v33
	global_store_dwordx2 v[92:93], v[12:13], off
	s_waitcnt vmcnt(19)
	v_pk_mul_f32 v[26:27], v[98:99], v[26:27]
	v_pk_mul_f32 v[28:29], v[100:101], v[28:29]
	v_pk_add_f32 v[4:5], v[162:163], 1.0 op_sel_hi:[1,0]
	v_pk_add_f32 v[10:11], v[164:165], 1.0 op_sel_hi:[1,0]
	v_pk_fma_f32 v[26:27], v[4:5], v[26:27], v[130:131]
	v_pk_fma_f32 v[28:29], v[10:11], v[28:29], v[132:133]
	v_cvt_pk_bf16_f32 v12, v26, v27
	v_cvt_pk_bf16_f32 v13, v28, v29
	global_store_dwordx2 v[92:93], v[12:13], off offset:512
	s_waitcnt vmcnt(17)
	v_pk_mul_f32 v[22:23], v[102:103], v[22:23]
	v_pk_mul_f32 v[24:25], v[104:105], v[24:25]
	v_pk_add_f32 v[4:5], v[166:167], 1.0 op_sel_hi:[1,0]
	v_pk_add_f32 v[10:11], v[168:169], 1.0 op_sel_hi:[1,0]
	v_pk_fma_f32 v[22:23], v[4:5], v[22:23], v[134:135]
	v_pk_fma_f32 v[24:25], v[10:11], v[24:25], v[136:137]
	v_cvt_pk_bf16_f32 v12, v22, v23
	v_cvt_pk_bf16_f32 v13, v24, v25
	global_store_dwordx2 v[92:93], v[12:13], off offset:1024
	s_waitcnt vmcnt(15)
	v_pk_mul_f32 v[18:19], v[106:107], v[18:19]
	v_pk_mul_f32 v[20:21], v[108:109], v[20:21]
	v_pk_add_f32 v[4:5], v[170:171], 1.0 op_sel_hi:[1,0]
	v_pk_add_f32 v[10:11], v[172:173], 1.0 op_sel_hi:[1,0]
	v_pk_fma_f32 v[18:19], v[4:5], v[18:19], v[138:139]
	v_pk_fma_f32 v[20:21], v[10:11], v[20:21], v[140:141]
	v_cvt_pk_bf16_f32 v12, v18, v19
	v_cvt_pk_bf16_f32 v13, v20, v21
	global_store_dwordx2 v[92:93], v[12:13], off offset:1536
	s_waitcnt vmcnt(13)
	v_pk_mul_f32 v[14:15], v[110:111], v[14:15]
	v_pk_mul_f32 v[16:17], v[112:113], v[16:17]
	v_pk_add_f32 v[4:5], v[174:175], 1.0 op_sel_hi:[1,0]
	v_pk_add_f32 v[10:11], v[176:177], 1.0 op_sel_hi:[1,0]
	v_pk_fma_f32 v[14:15], v[4:5], v[14:15], v[142:143]
	v_pk_fma_f32 v[16:17], v[10:11], v[16:17], v[144:145]
	v_cvt_pk_bf16_f32 v12, v14, v15
	v_cvt_pk_bf16_f32 v13, v16, v17
	global_store_dwordx2 v[92:93], v[12:13], off offset:2048
	s_waitcnt vmcnt(11)
	v_pk_mul_f32 v[6:7], v[114:115], v[6:7]
	v_pk_mul_f32 v[8:9], v[116:117], v[8:9]
	v_pk_add_f32 v[4:5], v[178:179], 1.0 op_sel_hi:[1,0]
	v_pk_add_f32 v[10:11], v[180:181], 1.0 op_sel_hi:[1,0]
	v_pk_fma_f32 v[6:7], v[4:5], v[6:7], v[146:147]
	v_pk_fma_f32 v[8:9], v[10:11], v[8:9], v[148:149]
	v_cvt_pk_bf16_f32 v12, v6, v7
	v_cvt_pk_bf16_f32 v13, v8, v9
	global_store_dwordx2 v[92:93], v[12:13], off offset:2560
	s_waitcnt vmcnt(9)
	v_pk_mul_f32 v[82:83], v[118:119], v[82:83]
	v_pk_mul_f32 v[84:85], v[120:121], v[84:85]
	v_pk_add_f32 v[4:5], v[182:183], 1.0 op_sel_hi:[1,0]
	v_pk_add_f32 v[10:11], v[184:185], 1.0 op_sel_hi:[1,0]
	v_pk_fma_f32 v[82:83], v[4:5], v[82:83], v[150:151]
	v_pk_fma_f32 v[84:85], v[10:11], v[84:85], v[152:153]
	v_cvt_pk_bf16_f32 v12, v82, v83
	v_cvt_pk_bf16_f32 v13, v84, v85
	global_store_dwordx2 v[92:93], v[12:13], off offset:3072
	s_waitcnt vmcnt(7)
	v_pk_mul_f32 v[86:87], v[122:123], v[86:87]
	v_pk_mul_f32 v[88:89], v[124:125], v[88:89]
	v_pk_add_f32 v[4:5], v[186:187], 1.0 op_sel_hi:[1,0]
	v_pk_add_f32 v[10:11], v[188:189], 1.0 op_sel_hi:[1,0]
	v_pk_fma_f32 v[86:87], v[4:5], v[86:87], v[154:155]
	v_pk_fma_f32 v[88:89], v[10:11], v[88:89], v[156:157]
	v_cvt_pk_bf16_f32 v12, v86, v87
	v_cvt_pk_bf16_f32 v13, v88, v89
	global_store_dwordx2 v[92:93], v[12:13], off offset:3584
	s_andn2_b64 exec, exec, s[8:9]
	s_cbranch_execz .LBB0_86
